# idx: the item's key-tile loads are issued before the LDS-protecting workgroup barrier
# baseline (speedup 1.0000x reference)
; #define LAS __attribute__((address_space(3)))
; __device__ __forceinline__ void idx_phase(const int TID, const int BID, PP p, LAS unsigned char* lds) {
;     ...
;     for (int item = BID; item < 1088; item += gridDim.x) {
;         const int b = item / 544; int rem = item % 544;
;         int a = 0; while (rem >= 4 * (a + 1)) { rem -= 4 * (a + 1); ++a; }
;         const int c = 4 * a + rem / (a + 1), kb = rem % (a + 1);
;         const int key0 = kb * 256, Nk = (c + 1) * 64, nkeys = min(256, Nk - key0);
;         bf16x8 Aq[4][4]; float wqa[4][16];
; #pragma unroll
;         for (int pr = 0; pr < 4; ++pr) {
;             const int tokq = b * SEQ + c * 64 + wv * 8 + 2 * pr;
;             const bf16_t* src = QIb + (size_t)(tokq + (rr >> 4)) * 1024 + (rr & 15) * 64 + g2 * 32;
; #pragma unroll
;             for (int ks = 0; ks < 4; ++ks) Aq[pr][ks] = *(const bf16x8*)(src + ks * 8);
; #pragma unroll
;             for (int i = 0; i < 16; ++i) wqa[pr][i] = WI[(size_t)(tokq + (i >> 3)) * 16 + 8 * ((i >> 2) & 1) + 4 * g2 + (i & 3)];
;         }
;         __syncthreads();
;         { const int key = t >> 1, half = t & 1;
;           if (key < nkeys) { const bf16_t* src = KIb + (size_t)(b * SEQ + key0 + key) * 64 + half * 32;
; #pragma unroll
;               for (int j = 0; j < 4; ++j) *(LAS u32x4*)(lds + key * 144 + half * 64 + j * 16) = *(const u32x4*)(src + j * 8); } }
.LBB0_731:
	v_mov_b32_e32 v0, v1
	v_mov_b32_e32 v199, v2
	v_mov_b32_e32 v198, v3
	v_mov_b32_e32 v197, v4
	s_mov_b32 s8, s4
	s_sub_i32 s4, s4, s10
	s_add_i32 s9, s9, 1
	s_add_i32 s11, s10, 4
	s_cmp_ge_i32 s8, s10
	v_add_u32_e32 v1, 0x100, v0
	v_add_u32_e32 v2, 0x100, v199
	v_add_u32_e32 v3, 0x100, v198
	v_add_u32_e32 v4, 0x100, v197
	s_mov_b32 s10, s11
	s_cbranch_scc1 .LBB0_731
	s_add_i32 s10, s9, 1
	v_cvt_f32_u32_e32 v1, s10
	s_not_b32 s12, s9
	s_abs_i32 s11, s8
	s_ashr_i32 s4, s8, 31
	v_rcp_iflag_f32_e32 v1, v1
	s_nop 0
	v_mul_f32_e32 v1, 0x4f7ffffe, v1
	v_cvt_u32_f32_e32 v1, v1
	s_nop 0
	v_readfirstlane_b32 s13, v1
	s_mul_i32 s12, s12, s13
	s_mul_hi_u32 s12, s13, s12
	s_add_i32 s13, s13, s12
	s_mul_hi_u32 s12, s11, s13
	s_mul_i32 s13, s12, s10
	s_sub_i32 s11, s11, s13
	s_add_i32 s14, s12, 1
	s_sub_i32 s13, s11, s10
	s_cmp_ge_u32 s11, s10
	s_cselect_b32 s12, s14, s12
	s_cselect_b32 s11, s13, s11
	s_add_i32 s13, s12, 1
	s_cmp_ge_u32 s11, s10
	s_cselect_b32 s11, s13, s12
	s_xor_b32 s14, s11, s4
	s_sub_i32 s11, s14, s4
	s_lshl_b32 s9, s9, 8
	s_lshl_b32 s12, s11, 6
	s_add_i32 s9, s12, s9
	s_add_i32 s12, s9, s1
	v_add_u32_e32 v2, s12, v178
	v_or_b32_e32 v4, v2, v179
	v_ashrrev_i32_e32 v5, 31, v4
	v_lshlrev_b64 v[4:5], 11, v[4:5]
	v_lshl_add_u64 v[4:5], v[166:167], 0, v[4:5]
	v_ashrrev_i32_e32 v3, 31, v2
	global_load_dwordx4 v[128:131], v[4:5], off
	global_load_dwordx4 v[132:135], v[4:5], off offset:16
	global_load_dwordx4 v[136:139], v[4:5], off offset:32
	global_load_dwordx4 v[140:143], v[4:5], off offset:48
	v_lshlrev_b64 v[4:5], 6, v[2:3]
	v_lshl_add_u64 v[4:5], v[170:171], 0, v[4:5]
	global_load_dwordx4 v[144:147], v[4:5], off
	global_load_dwordx4 v[148:151], v[4:5], off offset:32
	v_or_b32_e32 v4, 1, v2
	v_ashrrev_i32_e32 v5, 31, v4
	v_lshlrev_b64 v[4:5], 6, v[4:5]
	v_lshl_add_u64 v[4:5], v[170:171], 0, v[4:5]
	global_load_dwordx4 v[152:155], v[4:5], off
	global_load_dwordx4 v[156:159], v[4:5], off offset:32
	v_or_b32_e32 v4, 2, v2
	v_or_b32_e32 v6, v4, v179
	v_ashrrev_i32_e32 v7, 31, v6
	v_ashrrev_i32_e32 v5, 31, v4
	v_lshlrev_b64 v[6:7], 11, v[6:7]
	v_lshlrev_b64 v[4:5], 6, v[4:5]
	v_lshl_add_u64 v[6:7], v[166:167], 0, v[6:7]
	v_lshl_add_u64 v[4:5], v[170:171], 0, v[4:5]
	global_load_dwordx4 v[96:99], v[6:7], off
	global_load_dwordx4 v[100:103], v[6:7], off offset:16
	global_load_dwordx4 v[104:107], v[6:7], off offset:32
	global_load_dwordx4 v[108:111], v[6:7], off offset:48
	global_load_dwordx4 v[112:115], v[4:5], off
	global_load_dwordx4 v[116:119], v[4:5], off offset:32
	v_or_b32_e32 v4, 3, v2
	v_ashrrev_i32_e32 v5, 31, v4
	v_lshlrev_b64 v[4:5], 6, v[4:5]
	v_lshl_add_u64 v[4:5], v[170:171], 0, v[4:5]
	global_load_dwordx4 v[120:123], v[4:5], off
	global_load_dwordx4 v[124:127], v[4:5], off offset:32
	v_or_b32_e32 v4, 4, v2
	v_or_b32_e32 v6, v4, v179
	v_ashrrev_i32_e32 v7, 31, v6
	v_ashrrev_i32_e32 v5, 31, v4
	v_lshlrev_b64 v[6:7], 11, v[6:7]
	v_lshlrev_b64 v[4:5], 6, v[4:5]
	v_lshl_add_u64 v[6:7], v[166:167], 0, v[6:7]
	v_lshl_add_u64 v[4:5], v[170:171], 0, v[4:5]
	global_load_dwordx4 v[64:67], v[6:7], off
	global_load_dwordx4 v[68:71], v[6:7], off offset:16
	global_load_dwordx4 v[72:75], v[6:7], off offset:32
	global_load_dwordx4 v[76:79], v[6:7], off offset:48
	global_load_dwordx4 v[80:83], v[4:5], off
	global_load_dwordx4 v[84:87], v[4:5], off offset:32
	v_or_b32_e32 v4, 5, v2
	v_ashrrev_i32_e32 v5, 31, v4
	v_lshlrev_b64 v[4:5], 6, v[4:5]
	v_lshl_add_u64 v[4:5], v[170:171], 0, v[4:5]
	global_load_dwordx4 v[88:91], v[4:5], off
	global_load_dwordx4 v[92:95], v[4:5], off offset:32
	v_or_b32_e32 v4, 6, v2
	v_or_b32_e32 v6, v4, v179
	v_ashrrev_i32_e32 v7, 31, v6
	v_lshlrev_b64 v[6:7], 11, v[6:7]
	v_or_b32_e32 v2, 7, v2
	v_lshl_add_u64 v[6:7], v[166:167], 0, v[6:7]
	v_ashrrev_i32_e32 v5, 31, v4
	v_ashrrev_i32_e32 v3, 31, v2
	global_load_dwordx4 v[32:35], v[6:7], off
	global_load_dwordx4 v[36:39], v[6:7], off offset:16
	global_load_dwordx4 v[40:43], v[6:7], off offset:32
	global_load_dwordx4 v[44:47], v[6:7], off offset:48
	v_lshlrev_b64 v[4:5], 6, v[4:5]
	v_lshlrev_b64 v[2:3], 6, v[2:3]
	v_lshl_add_u64 v[4:5], v[170:171], 0, v[4:5]
	v_lshl_add_u64 v[2:3], v[170:171], 0, v[2:3]
	global_load_dwordx4 v[48:51], v[4:5], off
	global_load_dwordx4 v[52:55], v[4:5], off offset:32
	global_load_dwordx4 v[56:59], v[2:3], off
	global_load_dwordx4 v[60:63], v[2:3], off offset:32
	s_mul_i32 s11, s11, s10
	s_sub_i32 s8, s8, s11
	s_lshl_b32 s10, s8, 8
	s_sub_i32 s8, s9, s10
	s_add_i32 s8, s8, 64
	s_min_i32 s11, s8, 0x100
	v_cmp_gt_i32_e64 s[8:9], s11, v180
	s_and_saveexec_b64 s[12:13], s[8:9]
	s_add_i32 s1, s10, s1
	v_add_u32_e32 v2, s1, v180
	v_ashrrev_i32_e32 v3, 31, v2
	v_lshlrev_b64 v[2:3], 7, v[2:3]
	v_lshl_add_u64 v[14:15], v[168:169], 0, v[2:3]
	global_load_dwordx4 v[2:5], v[14:15], off
	global_load_dwordx4 v[6:9], v[14:15], off offset:16
	global_load_dwordx4 v[10:13], v[14:15], off offset:32
	s_nop 0
	global_load_dwordx4 v[14:17], v[14:15], off offset:48
	s_or_b64 exec, exec, s[12:13]
	s_barrier
	s_and_saveexec_b64 s[12:13], s[8:9]
	s_cbranch_execz .LBB0_734
	s_waitcnt vmcnt(3)
	ds_write_b128 v185, v[2:5]
	s_waitcnt vmcnt(2)
	ds_write_b128 v185, v[6:9] offset:16
	s_waitcnt vmcnt(1)
	ds_write_b128 v185, v[10:13] offset:32
	s_waitcnt vmcnt(0)
	ds_write_b128 v185, v[14:17] offset:48
